# SB item epilogue hand-written: 8 dwordx4 gate loads + 8 dwordx4 sc1 stores per lane (16 lanes per row piece) instead of 16 dwordx2 each, LDS reads batched
# baseline (speedup 1.0000x reference)
; DEV void sb_block(const Params& p, int item) {
;     ...
;   {
;     char* lw = smem + wave * 16384;
; #pragma unroll
;     for (int d = 0; d < 4; ++d)
; #pragma unroll
;       for (int q = 0; q < 4; ++q) {
;         const f32x4 o = {O[d][4 * q], O[d][4 * q + 1], O[d][4 * q + 2], O[d][4 * q + 3]};
;         *(f32x4*)(lw + l31 * 512 + (((8 * d + 2 * q + hh) ^ l31) * 16)) = o;
;       }
;     asm volatile("s_waitcnt lgkmcnt(0)" ::: "memory");
;     const size_t tok0 = row0 + qt * 32;
;     u32x2 gv[16];
; #pragma unroll
;     for (int i = 0; i < 16; ++i) { const int r = 2 * i + hh, c = l31 ^ r; gv[i] = __builtin_nontemporal_load((const u32x2*)(ssg + (tok0 + r) * 2048 + h * 128 + 4 * c)); }
.LBB0_571:
	v_readlane_b32 s0, v252, 13
	s_lshl_b32 s0, s0, 14
	s_add_i32 s4, s0, 0
	v_lshl_add_u32 v64, v203, 9, s4
	v_xor_b32_e32 v65, v202, v203
	v_lshl_add_u32 v66, v65, 4, v64
	s_waitcnt vmcnt(0)
	s_waitcnt vmcnt(0) lgkmcnt(0)
	s_barrier
	ds_write_b128 v66, v[48:51]
	v_bitop3_b32 v48, v202, v203, 2 bitop3:0x36
	v_lshl_add_u32 v49, v48, 4, v64
	ds_write_b128 v49, v[52:55]
	v_bitop3_b32 v49, v202, v203, 4 bitop3:0x36
	v_lshl_add_u32 v50, v49, 4, v64
	ds_write_b128 v50, v[56:59]
	v_bitop3_b32 v50, v202, v203, 6 bitop3:0x36
	v_lshl_add_u32 v51, v50, 4, v64
	ds_write_b128 v51, v[60:63]
	v_bitop3_b32 v51, v202, v203, 8 bitop3:0x36
	v_lshl_add_u32 v52, v51, 4, v64
	ds_write_b128 v52, v[32:35]
	v_bitop3_b32 v32, v202, v203, 10 bitop3:0x36
	v_lshl_add_u32 v33, v32, 4, v64
	ds_write_b128 v33, v[36:39]
	v_bitop3_b32 v33, v202, v203, 12 bitop3:0x36
	v_lshl_add_u32 v34, v33, 4, v64
	ds_write_b128 v34, v[40:43]
	v_bitop3_b32 v34, v202, v203, 14 bitop3:0x36
	v_lshl_add_u32 v35, v34, 4, v64
	ds_write_b128 v35, v[44:47]
	v_bitop3_b32 v35, v202, v203, 16 bitop3:0x36
	v_lshl_add_u32 v36, v35, 4, v64
	ds_write_b128 v36, v[16:19]
	v_bitop3_b32 v16, v202, v203, 18 bitop3:0x36
	v_lshl_add_u32 v17, v16, 4, v64
	ds_write_b128 v17, v[20:23]
	v_bitop3_b32 v17, v202, v203, 20 bitop3:0x36
	v_lshl_add_u32 v18, v17, 4, v64
	v_bitop3_b32 v20, v202, v203, 22 bitop3:0x36
	ds_write_b128 v18, v[24:27]
	v_lshl_add_u32 v18, v20, 4, v64
	v_bitop3_b32 v24, v202, v203, 24 bitop3:0x36
	ds_write_b128 v18, v[28:31]
	v_lshl_add_u32 v18, v24, 4, v64
	v_bitop3_b32 v98, v202, v203, 26 bitop3:0x36
	ds_write_b128 v18, v[0:3]
	v_lshl_add_u32 v0, v98, 4, v64
	ds_write_b128 v0, v[4:7]
	v_bitop3_b32 v4, v202, v203, 28 bitop3:0x36
	v_readlane_b32 s6, v252, 0
	v_lshl_add_u32 v0, v4, 4, v64
	v_bitop3_b32 v104, v202, v203, 30 bitop3:0x36
	v_readlane_b32 s7, v252, 1
	ds_write_b128 v0, v[8:11]
	v_lshl_add_u32 v0, v104, 4, v64
	v_readlane_b32 s0, v253, 48
	v_readlane_b32 s5, v254, 62
	v_readlane_b32 s7, v254, 63
	ds_write_b128 v0, v[12:15]
	v_readlane_b32 s1, v253, 49
	s_add_u32 s0, s0, s6
	v_or_b32_e32 v0, s5, v202
	v_mov_b32_e32 v1, s7
	s_addc_u32 s1, s1, 0
	v_lshlrev_b64 v[108:109], 12, v[0:1]
	v_lshl_add_u64 v[2:3], s[0:1], 0, v[108:109]
	v_lshlrev_b32_e32 v176, 3, v65
	s_waitcnt lgkmcnt(0)
	v_readlane_b32 s10, v253, 52
	v_readlane_b32 s11, v253, 53
	s_add_u32 s10, s10, s6
	s_addc_u32 s11, s11, 0
	v_and_b32_e32 v0, 15, v203
	v_lshrrev_b32_e32 v1, 4, v203
	v_lshl_or_b32 v2, v202, 1, v1
	v_lshlrev_b32_e32 v3, 9, v2
	v_lshl_add_u32 v3, v0, 5, v3
	v_lshl_add_u32 v3, v1, 4, v3
	v_add_u32_e32 v3, s4, v3
	v_xor_b32_e32 v4, 16, v3
	v_xor_b32_e32 v5, v0, v202
	v_or_b32_e32 v6, s5, v2
	v_lshlrev_b32_e32 v6, 12, v6
	v_lshl_add_u32 v8, v5, 4, v6
	global_load_dwordx4 v[16:19], v8, s[0:1] nt
	v_xor_b32_e32 v7, 2, v5
	v_lshl_add_u32 v9, v7, 4, v6
	v_add_u32_e32 v9, 0x4000, v9
	global_load_dwordx4 v[20:23], v9, s[0:1] nt
	v_xor_b32_e32 v7, 4, v5
	v_lshl_add_u32 v10, v7, 4, v6
	v_add_u32_e32 v10, 0x8000, v10
	global_load_dwordx4 v[24:27], v10, s[0:1] nt
	v_xor_b32_e32 v7, 6, v5
	v_lshl_add_u32 v11, v7, 4, v6
	v_add_u32_e32 v11, 0xc000, v11
	global_load_dwordx4 v[28:31], v11, s[0:1] nt
	v_xor_b32_e32 v7, 8, v5
	v_lshl_add_u32 v12, v7, 4, v6
	v_add_u32_e32 v12, 0x10000, v12
	global_load_dwordx4 v[32:35], v12, s[0:1] nt
	v_xor_b32_e32 v7, 10, v5
	v_lshl_add_u32 v13, v7, 4, v6
	v_add_u32_e32 v13, 0x14000, v13
	global_load_dwordx4 v[36:39], v13, s[0:1] nt
	v_xor_b32_e32 v7, 12, v5
	v_lshl_add_u32 v14, v7, 4, v6
	v_add_u32_e32 v14, 0x18000, v14
	global_load_dwordx4 v[40:43], v14, s[0:1] nt
	v_xor_b32_e32 v7, 14, v5
	v_lshl_add_u32 v15, v7, 4, v6
	v_add_u32_e32 v15, 0x1c000, v15
	global_load_dwordx4 v[44:47], v15, s[0:1] nt
	ds_read_b128 v[64:67], v3
	ds_read_b128 v[68:71], v4
	ds_read_b128 v[72:75], v3 offset:2048
	ds_read_b128 v[76:79], v4 offset:2048
	ds_read_b128 v[80:83], v3 offset:4096
	ds_read_b128 v[84:87], v4 offset:4096
	ds_read_b128 v[88:91], v3 offset:6144
	ds_read_b128 v[92:95], v4 offset:6144
	s_waitcnt vmcnt(7) lgkmcnt(6)
	v_lshlrev_b32_e32 v48, 16, v16
	v_and_b32_e32 v49, 0xffff0000, v16
	v_lshlrev_b32_e32 v50, 16, v17
	v_and_b32_e32 v51, 0xffff0000, v17
	v_lshlrev_b32_e32 v52, 16, v18
	v_and_b32_e32 v53, 0xffff0000, v18
	v_lshlrev_b32_e32 v54, 16, v19
	v_and_b32_e32 v55, 0xffff0000, v19
	v_pk_mul_f32 v[64:65], v[64:65], v[48:49]
	v_pk_mul_f32 v[66:67], v[66:67], v[50:51]
	v_pk_mul_f32 v[68:69], v[68:69], v[52:53]
	v_pk_mul_f32 v[70:71], v[70:71], v[54:55]
	v_cvt_pk_bf16_f32 v56, v64, v65
	v_cvt_pk_bf16_f32 v57, v66, v67
	v_cvt_pk_bf16_f32 v58, v68, v69
	v_cvt_pk_bf16_f32 v59, v70, v71
	global_store_dwordx4 v8, v[56:59], s[10:11] sc1
	s_waitcnt vmcnt(7) lgkmcnt(4)
	v_lshlrev_b32_e32 v48, 16, v20
	v_and_b32_e32 v49, 0xffff0000, v20
	v_lshlrev_b32_e32 v50, 16, v21
	v_and_b32_e32 v51, 0xffff0000, v21
	v_lshlrev_b32_e32 v52, 16, v22
	v_and_b32_e32 v53, 0xffff0000, v22
	v_lshlrev_b32_e32 v54, 16, v23
	v_and_b32_e32 v55, 0xffff0000, v23
	v_pk_mul_f32 v[72:73], v[72:73], v[48:49]
	v_pk_mul_f32 v[74:75], v[74:75], v[50:51]
	v_pk_mul_f32 v[76:77], v[76:77], v[52:53]
	v_pk_mul_f32 v[78:79], v[78:79], v[54:55]
	v_cvt_pk_bf16_f32 v56, v72, v73
	v_cvt_pk_bf16_f32 v57, v74, v75
	v_cvt_pk_bf16_f32 v58, v76, v77
	v_cvt_pk_bf16_f32 v59, v78, v79
	global_store_dwordx4 v9, v[56:59], s[10:11] sc1
	s_waitcnt vmcnt(7) lgkmcnt(2)
; DEV u32x2 pk4(f32x4 v) { u32x2 r = {pk_bf16(v[0], v[1]), pk_bf16(v[2], v[3])}; return r; }
; DEV f32x4 unpk4(u32x2 u) { f32x4 r = {bf_lo(u[0]), bf_hi(u[0]), bf_lo(u[1]), bf_hi(u[1])}; return r; }
; DEV void panel_publish(unsigned* cnt, const int tidx) {
;   asm volatile("s_waitcnt vmcnt(0)" ::: "memory");
;   __syncthreads();
;   if (tidx == 0) {
;     __builtin_amdgcn_fence(__ATOMIC_RELEASE, "agent");
;     asm volatile("s_waitcnt vmcnt(0)" ::: "memory");
;     __hip_atomic_fetch_add(cnt, 1u, __ATOMIC_RELAXED, __HIP_MEMORY_SCOPE_AGENT);
;   }
; }
; DEV void sb_block(const Params& p, int item) {
;     ...
;     for (int i = 0; i < 16; ++i) { const int r = 2 * i + hh, c = l31 ^ r; gv[i] = __builtin_nontemporal_load((const u32x2*)(ssg + (tok0 + r) * 2048 + h * 128 + 4 * c)); }
; #pragma unroll
;     for (int i = 0; i < 16; ++i) {
;       const int r = 2 * i + hh, c = l31 ^ r;
;       const f32x4 o = *(const f32x4*)(lw + r * 512 + l31 * 16);
;       *(u32x2*)(ob + (tok0 + r) * 2048 + h * 128 + 4 * c) = pk4(o * unpk4(gv[i]));
;     }
;   }
;   panel_publish((unsigned*)(p.ws + OFF_MISC + 2048 + 896) + (b * 8 + qb), tidx);
	v_lshlrev_b32_e32 v48, 16, v24
	v_and_b32_e32 v49, 0xffff0000, v24
	v_lshlrev_b32_e32 v50, 16, v25
	v_and_b32_e32 v51, 0xffff0000, v25
	v_lshlrev_b32_e32 v52, 16, v26
	v_and_b32_e32 v53, 0xffff0000, v26
	v_lshlrev_b32_e32 v54, 16, v27
	v_and_b32_e32 v55, 0xffff0000, v27
	v_pk_mul_f32 v[80:81], v[80:81], v[48:49]
	v_pk_mul_f32 v[82:83], v[82:83], v[50:51]
	v_pk_mul_f32 v[84:85], v[84:85], v[52:53]
	v_pk_mul_f32 v[86:87], v[86:87], v[54:55]
	v_cvt_pk_bf16_f32 v56, v80, v81
	v_cvt_pk_bf16_f32 v57, v82, v83
	v_cvt_pk_bf16_f32 v58, v84, v85
	v_cvt_pk_bf16_f32 v59, v86, v87
	global_store_dwordx4 v10, v[56:59], s[10:11] sc1
	s_waitcnt vmcnt(7) lgkmcnt(0)
	v_lshlrev_b32_e32 v48, 16, v28
	v_and_b32_e32 v49, 0xffff0000, v28
	v_lshlrev_b32_e32 v50, 16, v29
	v_and_b32_e32 v51, 0xffff0000, v29
	v_lshlrev_b32_e32 v52, 16, v30
	v_and_b32_e32 v53, 0xffff0000, v30
	v_lshlrev_b32_e32 v54, 16, v31
	v_and_b32_e32 v55, 0xffff0000, v31
	v_pk_mul_f32 v[88:89], v[88:89], v[48:49]
	v_pk_mul_f32 v[90:91], v[90:91], v[50:51]
	v_pk_mul_f32 v[92:93], v[92:93], v[52:53]
	v_pk_mul_f32 v[94:95], v[94:95], v[54:55]
	v_cvt_pk_bf16_f32 v56, v88, v89
	v_cvt_pk_bf16_f32 v57, v90, v91
	v_cvt_pk_bf16_f32 v58, v92, v93
	v_cvt_pk_bf16_f32 v59, v94, v95
	global_store_dwordx4 v11, v[56:59], s[10:11] sc1
	ds_read_b128 v[64:67], v3 offset:8192
	ds_read_b128 v[68:71], v4 offset:8192
	ds_read_b128 v[72:75], v3 offset:10240
	ds_read_b128 v[76:79], v4 offset:10240
	ds_read_b128 v[80:83], v3 offset:12288
	ds_read_b128 v[84:87], v4 offset:12288
	ds_read_b128 v[88:91], v3 offset:14336
	ds_read_b128 v[92:95], v4 offset:14336
	s_waitcnt vmcnt(7) lgkmcnt(6)
	v_lshlrev_b32_e32 v48, 16, v32
	v_and_b32_e32 v49, 0xffff0000, v32
	v_lshlrev_b32_e32 v50, 16, v33
	v_and_b32_e32 v51, 0xffff0000, v33
	v_lshlrev_b32_e32 v52, 16, v34
	v_and_b32_e32 v53, 0xffff0000, v34
	v_lshlrev_b32_e32 v54, 16, v35
	v_and_b32_e32 v55, 0xffff0000, v35
	v_pk_mul_f32 v[64:65], v[64:65], v[48:49]
	v_pk_mul_f32 v[66:67], v[66:67], v[50:51]
	v_pk_mul_f32 v[68:69], v[68:69], v[52:53]
	v_pk_mul_f32 v[70:71], v[70:71], v[54:55]
	v_cvt_pk_bf16_f32 v56, v64, v65
	v_cvt_pk_bf16_f32 v57, v66, v67
	v_cvt_pk_bf16_f32 v58, v68, v69
	v_cvt_pk_bf16_f32 v59, v70, v71
	global_store_dwordx4 v12, v[56:59], s[10:11] sc1
	s_waitcnt vmcnt(7) lgkmcnt(4)
	v_lshlrev_b32_e32 v48, 16, v36
	v_and_b32_e32 v49, 0xffff0000, v36
	v_lshlrev_b32_e32 v50, 16, v37
	v_and_b32_e32 v51, 0xffff0000, v37
	v_lshlrev_b32_e32 v52, 16, v38
	v_and_b32_e32 v53, 0xffff0000, v38
	v_lshlrev_b32_e32 v54, 16, v39
	v_and_b32_e32 v55, 0xffff0000, v39
	v_pk_mul_f32 v[72:73], v[72:73], v[48:49]
	v_pk_mul_f32 v[74:75], v[74:75], v[50:51]
	v_pk_mul_f32 v[76:77], v[76:77], v[52:53]
	v_pk_mul_f32 v[78:79], v[78:79], v[54:55]
	v_cvt_pk_bf16_f32 v56, v72, v73
	v_cvt_pk_bf16_f32 v57, v74, v75
	v_cvt_pk_bf16_f32 v58, v76, v77
	v_cvt_pk_bf16_f32 v59, v78, v79
	global_store_dwordx4 v13, v[56:59], s[10:11] sc1
	s_waitcnt vmcnt(7) lgkmcnt(2)
	v_lshlrev_b32_e32 v48, 16, v40
	v_and_b32_e32 v49, 0xffff0000, v40
	v_lshlrev_b32_e32 v50, 16, v41
	v_and_b32_e32 v51, 0xffff0000, v41
	v_lshlrev_b32_e32 v52, 16, v42
	v_and_b32_e32 v53, 0xffff0000, v42
	v_lshlrev_b32_e32 v54, 16, v43
	v_and_b32_e32 v55, 0xffff0000, v43
	v_pk_mul_f32 v[80:81], v[80:81], v[48:49]
	v_pk_mul_f32 v[82:83], v[82:83], v[50:51]
	v_pk_mul_f32 v[84:85], v[84:85], v[52:53]
	v_pk_mul_f32 v[86:87], v[86:87], v[54:55]
	v_cvt_pk_bf16_f32 v56, v80, v81
	v_cvt_pk_bf16_f32 v57, v82, v83
	v_cvt_pk_bf16_f32 v58, v84, v85
	v_cvt_pk_bf16_f32 v59, v86, v87
	global_store_dwordx4 v14, v[56:59], s[10:11] sc1
	s_waitcnt vmcnt(7) lgkmcnt(0)
	v_lshlrev_b32_e32 v48, 16, v44
	v_and_b32_e32 v49, 0xffff0000, v44
	v_lshlrev_b32_e32 v50, 16, v45
	v_and_b32_e32 v51, 0xffff0000, v45
	v_lshlrev_b32_e32 v52, 16, v46
	v_and_b32_e32 v53, 0xffff0000, v46
	v_lshlrev_b32_e32 v54, 16, v47
	v_and_b32_e32 v55, 0xffff0000, v47
	v_pk_mul_f32 v[88:89], v[88:89], v[48:49]
	v_pk_mul_f32 v[90:91], v[90:91], v[50:51]
	v_pk_mul_f32 v[92:93], v[92:93], v[52:53]
	v_pk_mul_f32 v[94:95], v[94:95], v[54:55]
	v_cvt_pk_bf16_f32 v56, v88, v89
	v_cvt_pk_bf16_f32 v57, v90, v91
	v_cvt_pk_bf16_f32 v58, v92, v93
	v_cvt_pk_bf16_f32 v59, v94, v95
	global_store_dwordx4 v15, v[56:59], s[10:11] sc1
	s_mov_b32 s0, s10
	s_mov_b32 s1, s11
	s_waitcnt vmcnt(0)
	v_cmp_eq_u32_e32 vcc, 0, v201
	s_barrier
	s_and_saveexec_b64 s[0:1], vcc
	s_cbranch_execz .LBB0_574
	s_mov_b64 s[4:5], exec
	v_mbcnt_lo_u32_b32 v0, s4, 0
	s_waitcnt vmcnt(0)
	s_waitcnt vmcnt(0)
	v_mbcnt_hi_u32_b32 v0, s5, v0
	v_cmp_eq_u32_e32 vcc, 0, v0
	s_and_b64 s[6:7], exec, vcc
	s_mov_b64 exec, s[6:7]
	s_cbranch_execz .LBB0_574
	v_readlane_b32 s6, v254, 61
	s_lshl_b32 s6, s6, 3
	v_readlane_b32 s7, v252, 6
	s_add_i32 s6, s6, s7
	s_bcnt1_i32_b64 s4, s[4:5]
	s_lshl_b32 s6, s6, 2
	v_mov_b32_e32 v1, s4
	v_readlane_b32 s4, v253, 42
	v_mov_b32_e32 v0, s6
	v_readlane_b32 s5, v253, 43
	s_nop 4
	global_atomic_add v0, v1, s[4:5]

; DEV void sb_block(const Params& p, int item) {
;     ...
;   {
;     char* lw = smem + wave * 16384;
; #pragma unroll
;     for (int d = 0; d < 4; ++d)
; #pragma unroll
;       for (int q = 0; q < 4; ++q) {
;         const f32x4 o = {O[d][4 * q], O[d][4 * q + 1], O[d][4 * q + 2], O[d][4 * q + 3]};
;         *(f32x4*)(lw + l31 * 512 + (((8 * d + 2 * q + hh) ^ l31) * 16)) = o;
;       }
;     asm volatile("s_waitcnt lgkmcnt(0)" ::: "memory");
;     const size_t tok0 = row0 + qt * 32;
;     u32x2 gv[16];
; #pragma unroll
;     for (int i = 0; i < 16; ++i) { const int r = 2 * i + hh, c = l31 ^ r; gv[i] = __builtin_nontemporal_load((const u32x2*)(ssg + (tok0 + r) * 2048 + h * 128 + 4 * c)); }
.LBB0_1223:
	s_lshl_b32 s0, s91, 14
	s_add_i32 s4, s0, 0
	v_lshl_add_u32 v64, v203, 9, s4
	v_xor_b32_e32 v65, v202, v203
	v_lshl_add_u32 v66, v65, 4, v64
	s_waitcnt vmcnt(0)
	s_waitcnt vmcnt(0) lgkmcnt(0)
	s_barrier
	ds_write_b128 v66, v[48:51]
	v_bitop3_b32 v48, v202, v203, 2 bitop3:0x36
	v_lshl_add_u32 v49, v48, 4, v64
	ds_write_b128 v49, v[52:55]
	v_bitop3_b32 v49, v202, v203, 4 bitop3:0x36
	v_lshl_add_u32 v50, v49, 4, v64
	ds_write_b128 v50, v[56:59]
	v_bitop3_b32 v50, v202, v203, 6 bitop3:0x36
	v_lshl_add_u32 v51, v50, 4, v64
	ds_write_b128 v51, v[60:63]
	v_bitop3_b32 v51, v202, v203, 8 bitop3:0x36
	v_lshl_add_u32 v52, v51, 4, v64
	ds_write_b128 v52, v[32:35]
	v_bitop3_b32 v32, v202, v203, 10 bitop3:0x36
	v_lshl_add_u32 v33, v32, 4, v64
	ds_write_b128 v33, v[36:39]
	v_bitop3_b32 v33, v202, v203, 12 bitop3:0x36
	v_lshl_add_u32 v34, v33, 4, v64
	ds_write_b128 v34, v[40:43]
	v_bitop3_b32 v34, v202, v203, 14 bitop3:0x36
	v_lshl_add_u32 v35, v34, 4, v64
	ds_write_b128 v35, v[44:47]
	v_bitop3_b32 v35, v202, v203, 16 bitop3:0x36
	v_lshl_add_u32 v36, v35, 4, v64
	ds_write_b128 v36, v[16:19]
	v_bitop3_b32 v16, v202, v203, 18 bitop3:0x36
	v_lshl_add_u32 v17, v16, 4, v64
	ds_write_b128 v17, v[20:23]
	v_bitop3_b32 v17, v202, v203, 20 bitop3:0x36
	v_lshl_add_u32 v18, v17, 4, v64
	v_bitop3_b32 v20, v202, v203, 22 bitop3:0x36
	ds_write_b128 v18, v[24:27]
	v_lshl_add_u32 v18, v20, 4, v64
	v_bitop3_b32 v24, v202, v203, 24 bitop3:0x36
	ds_write_b128 v18, v[28:31]
	v_lshl_add_u32 v18, v24, 4, v64
	v_bitop3_b32 v98, v202, v203, 26 bitop3:0x36
	ds_write_b128 v18, v[0:3]
	v_lshl_add_u32 v0, v98, 4, v64
	ds_write_b128 v0, v[4:7]
	v_bitop3_b32 v4, v202, v203, 28 bitop3:0x36
	v_lshl_add_u32 v0, v4, 4, v64
	v_bitop3_b32 v104, v202, v203, 30 bitop3:0x36
	ds_write_b128 v0, v[8:11]
	v_lshl_add_u32 v0, v104, 4, v64
	v_readlane_b32 s0, v253, 48
	v_readlane_b32 s6, v252, 0
	v_readlane_b32 s91, v254, 63
	v_readlane_b32 s5, v254, 62
	ds_write_b128 v0, v[12:15]
	v_readlane_b32 s1, v253, 49
	s_add_u32 s0, s0, s6
	v_or_b32_e32 v0, s91, v202
	v_mov_b32_e32 v1, s5
	s_addc_u32 s1, s1, 0
	v_lshlrev_b64 v[108:109], 12, v[0:1]
	v_lshl_add_u64 v[2:3], s[0:1], 0, v[108:109]
	v_lshlrev_b32_e32 v176, 3, v65
	s_waitcnt lgkmcnt(0)
	v_readlane_b32 s10, v253, 52
	v_readlane_b32 s11, v253, 53
	s_add_u32 s10, s10, s6
	s_addc_u32 s11, s11, 0
	v_and_b32_e32 v0, 15, v203
	v_lshrrev_b32_e32 v1, 4, v203
	v_lshl_or_b32 v2, v202, 1, v1
	v_lshlrev_b32_e32 v3, 9, v2
	v_lshl_add_u32 v3, v0, 5, v3
	v_lshl_add_u32 v3, v1, 4, v3
	v_add_u32_e32 v3, s4, v3
	v_xor_b32_e32 v4, 16, v3
	v_xor_b32_e32 v5, v0, v202
	v_or_b32_e32 v6, s91, v2
	v_lshlrev_b32_e32 v6, 12, v6
	v_lshl_add_u32 v8, v5, 4, v6
	global_load_dwordx4 v[16:19], v8, s[0:1] nt
	v_xor_b32_e32 v7, 2, v5
	v_lshl_add_u32 v9, v7, 4, v6
	v_add_u32_e32 v9, 0x4000, v9
	global_load_dwordx4 v[20:23], v9, s[0:1] nt
	v_xor_b32_e32 v7, 4, v5
	v_lshl_add_u32 v10, v7, 4, v6
	v_add_u32_e32 v10, 0x8000, v10
	global_load_dwordx4 v[24:27], v10, s[0:1] nt
	v_xor_b32_e32 v7, 6, v5
	v_lshl_add_u32 v11, v7, 4, v6
	v_add_u32_e32 v11, 0xc000, v11
	global_load_dwordx4 v[28:31], v11, s[0:1] nt
	v_xor_b32_e32 v7, 8, v5
	v_lshl_add_u32 v12, v7, 4, v6
	v_add_u32_e32 v12, 0x10000, v12
	global_load_dwordx4 v[32:35], v12, s[0:1] nt
	v_xor_b32_e32 v7, 10, v5
	v_lshl_add_u32 v13, v7, 4, v6
	v_add_u32_e32 v13, 0x14000, v13
	global_load_dwordx4 v[36:39], v13, s[0:1] nt
	v_xor_b32_e32 v7, 12, v5
	v_lshl_add_u32 v14, v7, 4, v6
	v_add_u32_e32 v14, 0x18000, v14
	global_load_dwordx4 v[40:43], v14, s[0:1] nt
	v_xor_b32_e32 v7, 14, v5
	v_lshl_add_u32 v15, v7, 4, v6
	v_add_u32_e32 v15, 0x1c000, v15
	global_load_dwordx4 v[44:47], v15, s[0:1] nt
	ds_read_b128 v[64:67], v3
	ds_read_b128 v[68:71], v4
	ds_read_b128 v[72:75], v3 offset:2048
	ds_read_b128 v[76:79], v4 offset:2048
	ds_read_b128 v[80:83], v3 offset:4096
	ds_read_b128 v[84:87], v4 offset:4096
	ds_read_b128 v[88:91], v3 offset:6144
	ds_read_b128 v[92:95], v4 offset:6144
	s_waitcnt vmcnt(7) lgkmcnt(6)
	v_lshlrev_b32_e32 v48, 16, v16
	v_and_b32_e32 v49, 0xffff0000, v16
	v_lshlrev_b32_e32 v50, 16, v17
	v_and_b32_e32 v51, 0xffff0000, v17
	v_lshlrev_b32_e32 v52, 16, v18
	v_and_b32_e32 v53, 0xffff0000, v18
	v_lshlrev_b32_e32 v54, 16, v19
	v_and_b32_e32 v55, 0xffff0000, v19
	v_pk_mul_f32 v[64:65], v[64:65], v[48:49]
	v_pk_mul_f32 v[66:67], v[66:67], v[50:51]
	v_pk_mul_f32 v[68:69], v[68:69], v[52:53]
	v_pk_mul_f32 v[70:71], v[70:71], v[54:55]
	v_cvt_pk_bf16_f32 v56, v64, v65
	v_cvt_pk_bf16_f32 v57, v66, v67
	v_cvt_pk_bf16_f32 v58, v68, v69
	v_cvt_pk_bf16_f32 v59, v70, v71
	global_store_dwordx4 v8, v[56:59], s[10:11] sc1
	s_waitcnt vmcnt(7) lgkmcnt(4)
	v_lshlrev_b32_e32 v48, 16, v20
	v_and_b32_e32 v49, 0xffff0000, v20
	v_lshlrev_b32_e32 v50, 16, v21
	v_and_b32_e32 v51, 0xffff0000, v21
	v_lshlrev_b32_e32 v52, 16, v22
	v_and_b32_e32 v53, 0xffff0000, v22
	v_lshlrev_b32_e32 v54, 16, v23
	v_and_b32_e32 v55, 0xffff0000, v23
	v_pk_mul_f32 v[72:73], v[72:73], v[48:49]
	v_pk_mul_f32 v[74:75], v[74:75], v[50:51]
	v_pk_mul_f32 v[76:77], v[76:77], v[52:53]
	v_pk_mul_f32 v[78:79], v[78:79], v[54:55]
	v_cvt_pk_bf16_f32 v56, v72, v73
	v_cvt_pk_bf16_f32 v57, v74, v75
	v_cvt_pk_bf16_f32 v58, v76, v77
	v_cvt_pk_bf16_f32 v59, v78, v79
	global_store_dwordx4 v9, v[56:59], s[10:11] sc1
	s_waitcnt vmcnt(7) lgkmcnt(2)
; DEV u32x2 pk4(f32x4 v) { u32x2 r = {pk_bf16(v[0], v[1]), pk_bf16(v[2], v[3])}; return r; }
; DEV f32x4 unpk4(u32x2 u) { f32x4 r = {bf_lo(u[0]), bf_hi(u[0]), bf_lo(u[1]), bf_hi(u[1])}; return r; }
; DEV void panel_publish(unsigned* cnt, const int tidx) {
;   asm volatile("s_waitcnt vmcnt(0)" ::: "memory");
;   __syncthreads();
;   if (tidx == 0) {
;     __builtin_amdgcn_fence(__ATOMIC_RELEASE, "agent");
;     asm volatile("s_waitcnt vmcnt(0)" ::: "memory");
;     __hip_atomic_fetch_add(cnt, 1u, __ATOMIC_RELAXED, __HIP_MEMORY_SCOPE_AGENT);
;   }
; }
; DEV void sb_block(const Params& p, int item) {
;     ...
;     for (int i = 0; i < 16; ++i) { const int r = 2 * i + hh, c = l31 ^ r; gv[i] = __builtin_nontemporal_load((const u32x2*)(ssg + (tok0 + r) * 2048 + h * 128 + 4 * c)); }
; #pragma unroll
;     for (int i = 0; i < 16; ++i) {
;       const int r = 2 * i + hh, c = l31 ^ r;
;       const f32x4 o = *(const f32x4*)(lw + r * 512 + l31 * 16);
;       *(u32x2*)(ob + (tok0 + r) * 2048 + h * 128 + 4 * c) = pk4(o * unpk4(gv[i]));
;     }
;   }
;   panel_publish((unsigned*)(p.ws + OFF_MISC + 2048 + 896) + (b * 8 + qb), tidx);
	v_lshlrev_b32_e32 v48, 16, v24
	v_and_b32_e32 v49, 0xffff0000, v24
	v_lshlrev_b32_e32 v50, 16, v25
	v_and_b32_e32 v51, 0xffff0000, v25
	v_lshlrev_b32_e32 v52, 16, v26
	v_and_b32_e32 v53, 0xffff0000, v26
	v_lshlrev_b32_e32 v54, 16, v27
	v_and_b32_e32 v55, 0xffff0000, v27
	v_pk_mul_f32 v[80:81], v[80:81], v[48:49]
	v_pk_mul_f32 v[82:83], v[82:83], v[50:51]
	v_pk_mul_f32 v[84:85], v[84:85], v[52:53]
	v_pk_mul_f32 v[86:87], v[86:87], v[54:55]
	v_cvt_pk_bf16_f32 v56, v80, v81
	v_cvt_pk_bf16_f32 v57, v82, v83
	v_cvt_pk_bf16_f32 v58, v84, v85
	v_cvt_pk_bf16_f32 v59, v86, v87
	global_store_dwordx4 v10, v[56:59], s[10:11] sc1
	s_waitcnt vmcnt(7) lgkmcnt(0)
	v_lshlrev_b32_e32 v48, 16, v28
	v_and_b32_e32 v49, 0xffff0000, v28
	v_lshlrev_b32_e32 v50, 16, v29
	v_and_b32_e32 v51, 0xffff0000, v29
	v_lshlrev_b32_e32 v52, 16, v30
	v_and_b32_e32 v53, 0xffff0000, v30
	v_lshlrev_b32_e32 v54, 16, v31
	v_and_b32_e32 v55, 0xffff0000, v31
	v_pk_mul_f32 v[88:89], v[88:89], v[48:49]
	v_pk_mul_f32 v[90:91], v[90:91], v[50:51]
	v_pk_mul_f32 v[92:93], v[92:93], v[52:53]
	v_pk_mul_f32 v[94:95], v[94:95], v[54:55]
	v_cvt_pk_bf16_f32 v56, v88, v89
	v_cvt_pk_bf16_f32 v57, v90, v91
	v_cvt_pk_bf16_f32 v58, v92, v93
	v_cvt_pk_bf16_f32 v59, v94, v95
	global_store_dwordx4 v11, v[56:59], s[10:11] sc1
	ds_read_b128 v[64:67], v3 offset:8192
	ds_read_b128 v[68:71], v4 offset:8192
	ds_read_b128 v[72:75], v3 offset:10240
	ds_read_b128 v[76:79], v4 offset:10240
	ds_read_b128 v[80:83], v3 offset:12288
	ds_read_b128 v[84:87], v4 offset:12288
	ds_read_b128 v[88:91], v3 offset:14336
	ds_read_b128 v[92:95], v4 offset:14336
	s_waitcnt vmcnt(7) lgkmcnt(6)
	v_lshlrev_b32_e32 v48, 16, v32
	v_and_b32_e32 v49, 0xffff0000, v32
	v_lshlrev_b32_e32 v50, 16, v33
	v_and_b32_e32 v51, 0xffff0000, v33
	v_lshlrev_b32_e32 v52, 16, v34
	v_and_b32_e32 v53, 0xffff0000, v34
	v_lshlrev_b32_e32 v54, 16, v35
	v_and_b32_e32 v55, 0xffff0000, v35
	v_pk_mul_f32 v[64:65], v[64:65], v[48:49]
	v_pk_mul_f32 v[66:67], v[66:67], v[50:51]
	v_pk_mul_f32 v[68:69], v[68:69], v[52:53]
	v_pk_mul_f32 v[70:71], v[70:71], v[54:55]
	v_cvt_pk_bf16_f32 v56, v64, v65
	v_cvt_pk_bf16_f32 v57, v66, v67
	v_cvt_pk_bf16_f32 v58, v68, v69
	v_cvt_pk_bf16_f32 v59, v70, v71
	global_store_dwordx4 v12, v[56:59], s[10:11] sc1
	s_waitcnt vmcnt(7) lgkmcnt(4)
	v_lshlrev_b32_e32 v48, 16, v36
	v_and_b32_e32 v49, 0xffff0000, v36
	v_lshlrev_b32_e32 v50, 16, v37
	v_and_b32_e32 v51, 0xffff0000, v37
	v_lshlrev_b32_e32 v52, 16, v38
	v_and_b32_e32 v53, 0xffff0000, v38
	v_lshlrev_b32_e32 v54, 16, v39
	v_and_b32_e32 v55, 0xffff0000, v39
	v_pk_mul_f32 v[72:73], v[72:73], v[48:49]
	v_pk_mul_f32 v[74:75], v[74:75], v[50:51]
	v_pk_mul_f32 v[76:77], v[76:77], v[52:53]
	v_pk_mul_f32 v[78:79], v[78:79], v[54:55]
	v_cvt_pk_bf16_f32 v56, v72, v73
	v_cvt_pk_bf16_f32 v57, v74, v75
	v_cvt_pk_bf16_f32 v58, v76, v77
	v_cvt_pk_bf16_f32 v59, v78, v79
	global_store_dwordx4 v13, v[56:59], s[10:11] sc1
	s_waitcnt vmcnt(7) lgkmcnt(2)
	v_lshlrev_b32_e32 v48, 16, v40
	v_and_b32_e32 v49, 0xffff0000, v40
	v_lshlrev_b32_e32 v50, 16, v41
	v_and_b32_e32 v51, 0xffff0000, v41
	v_lshlrev_b32_e32 v52, 16, v42
	v_and_b32_e32 v53, 0xffff0000, v42
	v_lshlrev_b32_e32 v54, 16, v43
	v_and_b32_e32 v55, 0xffff0000, v43
	v_pk_mul_f32 v[80:81], v[80:81], v[48:49]
	v_pk_mul_f32 v[82:83], v[82:83], v[50:51]
	v_pk_mul_f32 v[84:85], v[84:85], v[52:53]
	v_pk_mul_f32 v[86:87], v[86:87], v[54:55]
	v_cvt_pk_bf16_f32 v56, v80, v81
	v_cvt_pk_bf16_f32 v57, v82, v83
	v_cvt_pk_bf16_f32 v58, v84, v85
	v_cvt_pk_bf16_f32 v59, v86, v87
	global_store_dwordx4 v14, v[56:59], s[10:11] sc1
	s_waitcnt vmcnt(7) lgkmcnt(0)
	v_lshlrev_b32_e32 v48, 16, v44
	v_and_b32_e32 v49, 0xffff0000, v44
	v_lshlrev_b32_e32 v50, 16, v45
	v_and_b32_e32 v51, 0xffff0000, v45
	v_lshlrev_b32_e32 v52, 16, v46
	v_and_b32_e32 v53, 0xffff0000, v46
	v_lshlrev_b32_e32 v54, 16, v47
	v_and_b32_e32 v55, 0xffff0000, v47
	v_pk_mul_f32 v[88:89], v[88:89], v[48:49]
	v_pk_mul_f32 v[90:91], v[90:91], v[50:51]
	v_pk_mul_f32 v[92:93], v[92:93], v[52:53]
	v_pk_mul_f32 v[94:95], v[94:95], v[54:55]
	v_cvt_pk_bf16_f32 v56, v88, v89
	v_cvt_pk_bf16_f32 v57, v90, v91
	v_cvt_pk_bf16_f32 v58, v92, v93
	v_cvt_pk_bf16_f32 v59, v94, v95
	global_store_dwordx4 v15, v[56:59], s[10:11] sc1
	s_mov_b32 s0, s10
	s_mov_b32 s1, s11
	s_waitcnt vmcnt(0)
	v_cmp_eq_u32_e32 vcc, 0, v201
	v_readlane_b32 s7, v252, 1
	s_barrier
	s_and_saveexec_b64 s[0:1], vcc
	v_readlane_b32 s66, v254, 59
	s_mov_b32 s65, 0x800000
	v_readlane_b32 s67, v254, 60
	s_cbranch_execz .LBB0_1226
	s_mov_b64 s[4:5], exec
	v_mbcnt_lo_u32_b32 v0, s4, 0
	s_waitcnt vmcnt(0)
	s_waitcnt vmcnt(0)
	v_mbcnt_hi_u32_b32 v0, s5, v0
	v_cmp_eq_u32_e32 vcc, 0, v0
	s_and_b64 s[6:7], exec, vcc
	s_mov_b64 exec, s[6:7]
	s_cbranch_execz .LBB0_1226
	v_readlane_b32 s6, v252, 6
	s_lshl_b32 s6, s6, 3
	v_readlane_b32 s7, v252, 13
	s_add_i32 s6, s6, s7
	s_bcnt1_i32_b64 s4, s[4:5]
	s_lshl_b32 s6, s6, 2
	v_mov_b32_e32 v1, s4
	v_readlane_b32 s4, v253, 42
	v_mov_b32_e32 v0, s6
	v_readlane_b32 s5, v253, 43
	s_nop 4
	global_atomic_add v0, v1, s[4:5]
